# v38 plus stacked neutral levers: attention back-edge rotation, P1 norm wide stores, GEMM prologue batching, hyena pass-4 batching, tile-0 max3 chain
# speedup vs baseline: 1.0016x; 1.0016x over previous
; #define LOAD_TILE(ti, kreg, vreg) do { const int k0_ = TILE_K0(ti); const size_t grow_ = ((ti) < 4) ? (size_t)(M_ + b * LCTX + k0_) : (size_t)(b * SEQ + k0_); \
;         kreg = *(const u32x4*)(QKV + (grow_ + krow) * NQKV + 1024 + kvh * 64 + 8 * kch); vreg = *(const u32x4*)(QKV + (grow_ + lane) * NQKV + 1280 + kvh * 64 + 8 * w); } while (0)
; #define LOAD_TILE(ti, kreg, vreg) do { const int k0_ = TILE_K0(ti); const size_t grow_ = ((ti) < 4) ? (size_t)(M_ + b * LCTX + k0_) : (size_t)(b * SEQ + k0_); \
;         kreg = *(const u32x4*)(QKV + (grow_ + krow) * NQKV + 1024 + kvh * 64 + 8 * kch); vreg = *(const u32x4*)(QKV + (grow_ + lane) * NQKV + 1280 + kvh * 64 + 8 * w); } while (0)
; #define STAGE_NEXT(ti, vnext) do { if ((ti) + 1 < ntiles) STORE_TILE(((ti) + 1) & 1, vnext); \
;         kreg = kreg2; vreg = vreg2; kreg2 = kreg3; vreg2 = vreg3; \
;         if ((ti) + 4 < ntiles) LOAD_TILE((ti) + 4, kreg3, vreg3); } while (0)
;     ...
;         bf16x8 pa[4];
;         LOAD_TILE(0, kreg, vreg); STORE_TILE(0, 0); LOAD_TILE(1, kreg, vreg); LOAD_TILE(2, kreg2, vreg2); LOAD_TILE(3, kreg3, vreg3); __syncthreads();
;         {
;             QK_MAX(0, 0)
;             EXP_PACK();
;             if (resc) { _Pragma("unroll") for (int r = 0; r < 16; ++r) { o0[r] *= fres; o1[r] *= fres; } }
;             STAGE_NEXT(0, 1);
;             __syncthreads();
.LBB0_506:
	v_exp_f32_e32 v1, v18
	v_exp_f32_e32 v46, v2
	v_exp_f32_e32 v47, v19
	v_exp_f32_e32 v48, v3
	v_exp_f32_e32 v49, v20
	v_add_f32_e32 v2, v46, v1
	v_exp_f32_e32 v50, v4
	v_add_f32_e32 v2, 0, v2
	v_add_f32_e32 v3, v48, v47
	v_exp_f32_e32 v51, v21
	v_exp_f32_e32 v52, v5
	v_add_f32_e32 v18, v3, v2
	v_exp_f32_e32 v3, v22
	v_exp_f32_e32 v5, v6
	v_exp_f32_e32 v2, v23
	v_exp_f32_e32 v4, v7
	v_add_f32_e32 v19, v50, v49
	v_add_f32_e32 v6, v19, v18
	v_add_f32_e32 v7, v52, v51
	v_add_f32_e32 v18, v7, v6
	v_pk_add_f32 v[6:7], v[4:5], v[2:3]
	v_exp_f32_e32 v19, v24
	v_add_f32_e32 v7, v7, v18
	v_exp_f32_e32 v21, v8
	v_exp_f32_e32 v18, v25
	v_exp_f32_e32 v20, v9
	v_add_f32_e32 v8, v6, v7
	v_exp_f32_e32 v9, v26
	v_exp_f32_e32 v23, v10
	v_pk_add_f32 v[6:7], v[20:21], v[18:19]
	v_exp_f32_e32 v22, v11
	v_add_f32_e32 v7, v7, v8
	v_exp_f32_e32 v8, v27
	s_lshl_b32 s8, s25, 6
	s_sub_i32 s25, 0x80, s13
	s_lshl_b32 s56, s38, 6
	s_and_b32 s39, s44, 0x1fc0
	s_ashr_i32 s33, s25, 6
	s_cmpk_lt_u32 s13, 0x80
	v_pk_mov_b32 v[10:11], v[18:19], v[18:19] op_sel:[1,0]
	v_pk_mov_b32 v[18:19], v[20:21], v[20:21] op_sel:[1,0]
	v_add_f32_e32 v20, v6, v7
	v_pk_add_f32 v[6:7], v[22:23], v[8:9]
	s_cselect_b32 s57, s33, 0
	s_sub_i32 s33, 0x2040, s13
	v_add_f32_e32 v7, v7, v20
	v_exp_f32_e32 v21, v28
	v_exp_f32_e32 v25, v12
	v_exp_f32_e32 v20, v29
	v_exp_f32_e32 v24, v13
	s_lshr_b32 s33, s33, 6
	s_cmpk_gt_u32 s13, 0x1f40
	s_cselect_b32 s33, s33, 4
	s_sub_i32 s58, s33, s57
	v_pk_mov_b32 v[12:13], v[22:23], v[22:23] op_sel:[1,0]
	v_add_f32_e32 v22, v6, v7
	v_pk_add_f32 v[6:7], v[24:25], v[20:21]
	s_lshl_b32 s33, s57, 6
	v_add_f32_e32 v7, v7, v22
	v_exp_f32_e32 v23, v30
	v_exp_f32_e32 v27, v14
	v_exp_f32_e32 v22, v31
	v_exp_f32_e32 v26, v15
	s_add_i32 s24, s24, s33
	s_add_i32 s13, s13, s24
	s_add_i32 s40, s13, 0xffffff80
	s_ashr_i32 s41, s40, 31
	v_pk_mov_b32 v[14:15], v[20:21], v[20:21] op_sel:[1,0]
	v_pk_mov_b32 v[20:21], v[24:25], v[24:25] op_sel:[1,0]
	v_add_f32_e32 v24, v6, v7
	v_pk_add_f32 v[6:7], v[26:27], v[22:23]
	v_exp_f32_e32 v29, v16
	v_or_b32_e32 v16, s40, v144
	v_mov_b64_e32 v[30:31], s[4:5]
	v_lshl_add_u64 v[44:45], s[40:41], 0, v[154:155]
	v_add_f32_e32 v7, v7, v24
	v_exp_f32_e32 v25, v32
	v_exp_f32_e32 v24, v33
	v_mad_i64_i32 v[32:33], s[62:63], v16, s46, v[30:31]
	s_lshl_b32 s8, s8, 1
	v_mad_u64_u32 v[30:31], s[40:41], v44, s46, v[30:31]
	v_lshl_add_u64 v[32:33], v[32:33], 0, s[8:9]
	s_mov_b32 s13, s9
	v_mad_i32_i24 v31, v45, s46, v31
	v_lshl_add_u64 v[32:33], v[32:33], 0, s[12:13]
	v_lshl_add_u64 v[30:31], v[30:31], 0, s[8:9]
	v_mov_b32_e32 v165, v147
	v_lshl_add_u64 v[30:31], v[30:31], 0, v[164:165]
	global_load_dwordx4 v[112:115], v[32:33], off offset:2560
	global_load_dwordx4 v[116:119], v[30:31], off offset:2048
	v_exp_f32_e32 v28, v17
	v_pk_mov_b32 v[16:17], v[22:23], v[22:23] op_sel:[1,0]
	v_pk_mov_b32 v[22:23], v[26:27], v[26:27] op_sel:[1,0]
	v_add_f32_e32 v26, v6, v7
	v_pk_add_f32 v[6:7], v[28:29], v[24:25]
	v_cvt_pk_bf16_f32 v130, v16, v17
	v_add_f32_e32 v7, v7, v26
	v_cndmask_b32_e64 v16, v42, 0, s[22:23]
	s_add_i32 s13, s58, 4
	v_pk_mov_b32 v[24:25], v[24:25], v[24:25] op_sel:[1,0]
	v_pk_mov_b32 v[26:27], v[28:29], v[28:29] op_sel:[1,0]
	v_add_f32_e32 v6, v6, v7
	v_mov_b32_e32 v30, v16
	v_mov_b32_e32 v31, v16
	s_add_u32 s22, s42, s8
	v_pk_mov_b32 v[2:3], v[2:3], v[2:3] op_sel:[1,0]
	v_pk_mov_b32 v[4:5], v[4:5], v[4:5] op_sel:[1,0]
	v_pk_mov_b32 v[8:9], v[8:9], v[8:9] op_sel:[1,0]
	v_add_f32_e32 v165, v43, v6
	v_cvt_pk_bf16_f32 v132, v1, v47
	v_cvt_pk_bf16_f32 v131, v24, v25
	v_cvt_pk_bf16_f32 v124, v46, v48
	v_cvt_pk_bf16_f32 v127, v18, v19
	v_cvt_pk_bf16_f32 v121, v20, v21
	v_cvt_pk_bf16_f32 v122, v22, v23
	v_cvt_pk_bf16_f32 v123, v26, v27
	v_mov_b32_e32 v17, v16
	v_mov_b32_e32 v18, v16
	v_mov_b32_e32 v19, v16
	v_mov_b32_e32 v20, v16
	v_mov_b32_e32 v21, v16
	v_mov_b32_e32 v22, v16
	v_mov_b32_e32 v23, v16
	v_mov_b32_e32 v24, v16
	v_mov_b32_e32 v25, v16
	v_mov_b32_e32 v26, v16
	v_mov_b32_e32 v27, v16
	v_mov_b32_e32 v28, v16
	v_mov_b32_e32 v29, v16
	s_waitcnt vmcnt(7)
	ds_write_b128 v177, v[38:41] offset:9216
	s_waitcnt vmcnt(6)
	v_and_b32_e32 v200, 1, v152
	v_mul_u32_u24_e32 v200, 0x21e, v200
	v_add_u32_e32 v201, v200, v178
	s_mov_b64 s[92:93], vcc
	s_mov_b64 vcc, s[88:89]
	v_cndmask_b32_dpp v192, v36, v34, vcc quad_perm:[1,0,3,2] row_mask:0xf bank_mask:0xf
	v_cndmask_b32_dpp v193, v37, v35, vcc quad_perm:[1,0,3,2] row_mask:0xf bank_mask:0xf
	s_mov_b64 vcc, s[90:91]
	v_cndmask_b32_dpp v194, v34, v36, vcc quad_perm:[1,0,3,2] row_mask:0xf bank_mask:0xf
	v_cndmask_b32_dpp v195, v35, v37, vcc quad_perm:[1,0,3,2] row_mask:0xf bank_mask:0xf
	v_and_b32_e32 v196, 0xffff, v192
	v_lshl_or_b32 v196, v194, 16, v196
	v_lshrrev_b32_e32 v197, 16, v192
	v_and_or_b32 v197, v194, s70, v197
	v_and_b32_e32 v198, 0xffff, v193
	v_lshl_or_b32 v198, v195, 16, v198
	v_lshrrev_b32_e32 v199, 16, v193
	v_and_or_b32 v199, v195, s70, v199
	s_mov_b64 vcc, s[92:93]
	ds_write_b32 v201, v196 offset:27136
	ds_write_b32 v201, v197 offset:27272
	ds_write_b32 v201, v198 offset:27408
	ds_write_b32 v201, v199 offset:27544
	s_addc_u32 s23, s43, 0
	s_add_i32 s24, s24, s39
	v_mov_b64_e32 v[46:47], v[30:31]
	v_ashrrev_i32_e32 v171, 31, v170
	s_mov_b32 s25, 0
	v_cvt_pk_bf16_f32 v133, v49, v51
	v_cvt_pk_bf16_f32 v134, v2, v3
	v_cvt_pk_bf16_f32 v135, v10, v11
	v_cvt_pk_bf16_f32 v128, v8, v9
	v_cvt_pk_bf16_f32 v129, v14, v15
	v_cvt_pk_bf16_f32 v125, v50, v52
	v_cvt_pk_bf16_f32 v126, v4, v5
	v_cvt_pk_bf16_f32 v120, v12, v13
	s_mov_b32 s38, 1
	v_lshl_add_u64 v[172:173], v[158:159], 0, s[8:9]
	s_sub_i32 s24, s24, 64
	v_subrev_u32_e32 v167, s33, v179
	v_mov_b64_e32 v[44:45], v[28:29]
	v_mov_b64_e32 v[42:43], v[26:27]
	v_mov_b64_e32 v[40:41], v[24:25]
	v_mov_b64_e32 v[38:39], v[22:23]
	v_mov_b64_e32 v[36:37], v[20:21]
	v_mov_b64_e32 v[34:35], v[18:19]
	v_mov_b64_e32 v[32:33], v[16:17]
	s_mov_b32 s62, 0
	v_mov_b32_e32 v1, v0
	v_mov_b32_e32 v2, v0
	v_mov_b32_e32 v3, v0
	v_mov_b32_e32 v4, v0
	v_mov_b32_e32 v5, v0
	v_mov_b32_e32 v6, v0
	v_mov_b32_e32 v7, v0
	v_mov_b32_e32 v8, v0
	v_mov_b32_e32 v9, v0
	v_mov_b32_e32 v10, v0
	v_mov_b32_e32 v11, v0
	v_mov_b32_e32 v12, v0
	v_mov_b32_e32 v13, v0
	v_mov_b32_e32 v14, v0
	v_mov_b32_e32 v15, v0
	s_waitcnt lgkmcnt(0)
	s_add_i32 s8, s25, 1
	s_bitcmp1_b32 s8, 0
	s_cselect_b32 s33, 0x2400, 0
	v_add_u32_e32 v153, s33, v145
